# v31 + ret_sample streaming loop with 32 row loads in flight + P8 chunk-state scan with 16 chunk loads in flight (same arithmetic order)
# speedup vs baseline: 1.0068x; 1.0068x over previous
; #define LAS __attribute__((address_space(3)))
; DI void ret_sample_item(const Params& p, LAS unsigned char* ldsb, int item) {
;     ...
;     const float score = wave_sum(sp);
;     const float g = 1.0f - exp2f(-5.0f - (float)h);
;     const float* sin = p.in[8] + (size_t)(b * 4 + h) * 65536; float* sout = p.out + O_RETS + (size_t)(b * 4 + h) * 65536;
;     const int dv4 = lane * 4;
;     const f32x4 v4 = *(const LAS f32x4*)(vs + dv4);
;     f32x4 cr = (f32x4){0.f, 0.f, 0.f, 0.f};
; #pragma unroll 8
;     for (int i = 0; i < 32; ++i) { const int dk = wid + 8 * i; const f32x4 s4 = __builtin_nontemporal_load((const f32x4*)(sin + (size_t)dk * 256 + dv4));
;         cr += s4 * qs[dk]; __builtin_nontemporal_store(s4 * g + v4 * ks[dk], (f32x4*)(sout + (size_t)dk * 256 + dv4)); }
.LBB0_1945:
	s_or_b64 exec, exec, s[42:43]
	v_and_b32_e32 v35, 63, v12
	v_lshl_add_u32 v8, v35, 2, 0
	s_waitcnt lgkmcnt(0)
	s_barrier
	ds_read2st64_b32 v[0:1], v8 offset1:1
	ds_read2st64_b32 v[2:3], v8 offset0:4 offset1:5
	ds_read2st64_b32 v[4:5], v8 offset0:6 offset1:7
	ds_read2st64_b32 v[6:7], v8 offset0:2 offset1:3
	v_cmp_lt_i32_e32 vcc, v26, v25
	s_ashr_i32 s19, s18, 31
	s_waitcnt lgkmcnt(2)
	v_fma_f32 v0, v0, v2, 0
	v_fmac_f32_e32 v0, v1, v3
	s_waitcnt lgkmcnt(0)
	v_fmac_f32_e32 v0, v6, v4
	v_cndmask_b32_e32 v1, v24, v26, vcc
	v_fmac_f32_e32 v0, v7, v5
	v_lshlrev_b32_e32 v36, 2, v1
	ds_bpermute_b32 v1, v36, v0
	v_cmp_lt_i32_e32 vcc, v27, v25
	v_ashrrev_i32_e32 v14, 6, v12
	v_ashrrev_i32_e32 v15, 31, v14
	s_waitcnt lgkmcnt(0)
	v_add_f32_e32 v0, v0, v1
	v_cndmask_b32_e32 v1, v24, v27, vcc
	v_lshlrev_b32_e32 v37, 2, v1
	ds_bpermute_b32 v1, v37, v0
	v_cmp_lt_i32_e32 vcc, v28, v25
	s_waitcnt lgkmcnt(0)
	v_add_f32_e32 v0, v0, v1
	v_cndmask_b32_e32 v1, v24, v28, vcc
	v_lshlrev_b32_e32 v38, 2, v1
	ds_bpermute_b32 v1, v38, v0
	v_cmp_lt_i32_e32 vcc, v29, v25
	s_waitcnt lgkmcnt(0)
	v_add_f32_e32 v1, v0, v1
	v_cndmask_b32_e32 v0, v24, v29, vcc
	v_lshlrev_b32_e32 v39, 2, v0
	ds_bpermute_b32 v2, v39, v1
	v_cmp_lt_i32_e32 vcc, v30, v25
	v_mov_b32_e32 v0, 0
	s_waitcnt lgkmcnt(0)
	v_add_f32_e32 v41, v1, v2
	v_cndmask_b32_e32 v1, v24, v30, vcc
	v_lshlrev_b32_e32 v40, 2, v1
	v_cvt_f32_ubyte0_e32 v1, s66
	v_sub_f32_e32 v1, 0xc0a00000, v1
	v_cmp_gt_f32_e32 vcc, s46, v1
	s_and_b64 s[42:43], vcc, exec
	s_cselect_b32 s42, 0xffffffc0, 0
	v_cndmask_b32_e32 v2, 0, v31, vcc
	v_add_f32_e32 v1, v1, v2
	v_exp_f32_e32 v1, v1
	ds_bpermute_b32 v42, v40, v41
	v_lshlrev_b64 v[2:3], 10, v[14:15]
	v_lshl_or_b32 v2, v35, 4, v2
	v_ldexp_f32 v1, v1, s42
	v_sub_f32_e32 v16, 1.0, v1
	v_mad_u32_u24 v1, v35, 12, v8
	ds_read_b128 v[4:7], v1 offset:2048
	v_mov_b32_e32 v17, v16
	v_lshl_add_u64 v[18:19], s[12:13], 0, v[2:3]
	v_lshl_add_u64 v[20:21], s[16:17], 0, v[2:3]
	v_lshl_add_u32 v15, v14, 2, 0
	s_mov_b64 s[42:43], 0
	v_mov_b32_e32 v22, v16
	v_mov_b32_e32 v23, v16
	v_mov_b32_e32 v1, v0
	v_mov_b32_e32 v2, v0
	v_mov_b32_e32 v3, v0
	s_mov_b32 s42, 0x2000
	s_mov_b32 s43, 0
	s_mov_b32 s48, 0x86c4000
	s_mov_b32 s49, 0
	v_mov_b64_e32 v[84:85], v[20:21]
	global_load_dwordx4 v[88:91], v[84:85], off nt
	v_lshl_add_u64 v[84:85], v[84:85], 0, s[42:43]
	global_load_dwordx4 v[92:95], v[84:85], off nt
	v_lshl_add_u64 v[84:85], v[84:85], 0, s[42:43]
	global_load_dwordx4 v[96:99], v[84:85], off nt
	v_lshl_add_u64 v[84:85], v[84:85], 0, s[42:43]
	global_load_dwordx4 v[100:103], v[84:85], off nt
	v_lshl_add_u64 v[84:85], v[84:85], 0, s[42:43]
	global_load_dwordx4 v[104:107], v[84:85], off nt
	v_lshl_add_u64 v[84:85], v[84:85], 0, s[42:43]
	global_load_dwordx4 v[108:111], v[84:85], off nt
	v_lshl_add_u64 v[84:85], v[84:85], 0, s[42:43]
	global_load_dwordx4 v[112:115], v[84:85], off nt
	v_lshl_add_u64 v[84:85], v[84:85], 0, s[42:43]
	global_load_dwordx4 v[116:119], v[84:85], off nt
	v_lshl_add_u64 v[84:85], v[84:85], 0, s[42:43]
	global_load_dwordx4 v[120:123], v[84:85], off nt
	v_lshl_add_u64 v[84:85], v[84:85], 0, s[42:43]
	global_load_dwordx4 v[124:127], v[84:85], off nt
	v_lshl_add_u64 v[84:85], v[84:85], 0, s[42:43]
	global_load_dwordx4 v[128:131], v[84:85], off nt
	v_lshl_add_u64 v[84:85], v[84:85], 0, s[42:43]
	global_load_dwordx4 v[132:135], v[84:85], off nt
	v_lshl_add_u64 v[84:85], v[84:85], 0, s[42:43]
	global_load_dwordx4 v[136:139], v[84:85], off nt
	v_lshl_add_u64 v[84:85], v[84:85], 0, s[42:43]
	global_load_dwordx4 v[140:143], v[84:85], off nt
	v_lshl_add_u64 v[84:85], v[84:85], 0, s[42:43]
	global_load_dwordx4 v[144:147], v[84:85], off nt
	v_lshl_add_u64 v[84:85], v[84:85], 0, s[42:43]
	global_load_dwordx4 v[152:155], v[84:85], off nt
	v_lshl_add_u64 v[84:85], v[84:85], 0, s[42:43]
	global_load_dwordx4 v[156:159], v[84:85], off nt
	v_lshl_add_u64 v[84:85], v[84:85], 0, s[42:43]
	global_load_dwordx4 v[160:163], v[84:85], off nt
	v_lshl_add_u64 v[84:85], v[84:85], 0, s[42:43]
	global_load_dwordx4 v[164:167], v[84:85], off nt
	v_lshl_add_u64 v[84:85], v[84:85], 0, s[42:43]
	global_load_dwordx4 v[168:171], v[84:85], off nt
	v_lshl_add_u64 v[84:85], v[84:85], 0, s[42:43]
	global_load_dwordx4 v[172:175], v[84:85], off nt
	v_lshl_add_u64 v[84:85], v[84:85], 0, s[42:43]
	global_load_dwordx4 v[176:179], v[84:85], off nt
	v_lshl_add_u64 v[84:85], v[84:85], 0, s[42:43]
	global_load_dwordx4 v[180:183], v[84:85], off nt
	v_lshl_add_u64 v[84:85], v[84:85], 0, s[42:43]
	global_load_dwordx4 v[184:187], v[84:85], off nt
	v_lshl_add_u64 v[84:85], v[84:85], 0, s[42:43]
	global_load_dwordx4 v[188:191], v[84:85], off nt
	v_lshl_add_u64 v[84:85], v[84:85], 0, s[42:43]
	global_load_dwordx4 v[192:195], v[84:85], off nt
	v_lshl_add_u64 v[84:85], v[84:85], 0, s[42:43]
	global_load_dwordx4 v[196:199], v[84:85], off nt
	v_lshl_add_u64 v[84:85], v[84:85], 0, s[42:43]
	global_load_dwordx4 v[200:203], v[84:85], off nt
	v_lshl_add_u64 v[84:85], v[84:85], 0, s[42:43]
	global_load_dwordx4 v[204:207], v[84:85], off nt
	v_lshl_add_u64 v[84:85], v[84:85], 0, s[42:43]
	global_load_dwordx4 v[208:211], v[84:85], off nt
	v_lshl_add_u64 v[84:85], v[84:85], 0, s[42:43]
	global_load_dwordx4 v[212:215], v[84:85], off nt
	v_lshl_add_u64 v[84:85], v[84:85], 0, s[42:43]
	global_load_dwordx4 v[216:219], v[84:85], off nt
	v_add_u32_e32 v43, 0x400, v15
	ds_read2_b32 v[44:45], v43 offset0:0 offset1:8
	ds_read2_b32 v[46:47], v43 offset0:16 offset1:24
	ds_read2_b32 v[48:49], v43 offset0:32 offset1:40
	ds_read2_b32 v[50:51], v43 offset0:48 offset1:56
	ds_read2_b32 v[52:53], v43 offset0:64 offset1:72
	ds_read2_b32 v[54:55], v43 offset0:80 offset1:88
	ds_read2_b32 v[56:57], v43 offset0:96 offset1:104
	ds_read2_b32 v[58:59], v43 offset0:112 offset1:120
	ds_read2_b32 v[60:61], v43 offset0:128 offset1:136
	ds_read2_b32 v[62:63], v43 offset0:144 offset1:152
	ds_read2_b32 v[64:65], v43 offset0:160 offset1:168
	ds_read2_b32 v[66:67], v43 offset0:176 offset1:184
	ds_read2_b32 v[68:69], v43 offset0:192 offset1:200
	ds_read2_b32 v[70:71], v43 offset0:208 offset1:216
	ds_read2_b32 v[72:73], v43 offset0:224 offset1:232
	ds_read2_b32 v[74:75], v43 offset0:240 offset1:248
	v_lshl_add_u64 v[86:87], v[18:19], 0, s[48:49]
	s_waitcnt lgkmcnt(0)
; DI void ret_sample_item(const Params& p, LAS unsigned char* ldsb, int item) {
;     ...
;     for (int i = 0; i < 32; ++i) { const int dk = wid + 8 * i; const f32x4 s4 = __builtin_nontemporal_load((const f32x4*)(sin + (size_t)dk * 256 + dv4));
;         cr += s4 * qs[dk]; __builtin_nontemporal_store(s4 * g + v4 * ks[dk], (f32x4*)(sout + (size_t)dk * 256 + dv4)); }
	s_waitcnt vmcnt(31)
	v_mul_f32_e32 v76, v4, v44
	v_mul_f32_e32 v77, v5, v44
	v_mul_f32_e32 v78, v6, v44
	v_mul_f32_e32 v79, v7, v44
	v_fmac_f32_e32 v76, v16, v88
	v_fmac_f32_e32 v77, v16, v89
	v_fmac_f32_e32 v78, v16, v90
	v_fmac_f32_e32 v79, v16, v91
	global_store_dwordx4 v[86:87], v[76:79], off nt
	v_lshl_add_u64 v[86:87], v[86:87], 0, s[42:43]
	s_waitcnt vmcnt(31)
	v_mul_f32_e32 v80, v4, v45
	v_mul_f32_e32 v81, v5, v45
	v_mul_f32_e32 v82, v6, v45
	v_mul_f32_e32 v83, v7, v45
	v_fmac_f32_e32 v80, v16, v92
	v_fmac_f32_e32 v81, v16, v93
	v_fmac_f32_e32 v82, v16, v94
	v_fmac_f32_e32 v83, v16, v95
	global_store_dwordx4 v[86:87], v[80:83], off nt
	v_lshl_add_u64 v[86:87], v[86:87], 0, s[42:43]
	s_waitcnt vmcnt(31)
	v_mul_f32_e32 v76, v4, v46
	v_mul_f32_e32 v77, v5, v46
	v_mul_f32_e32 v78, v6, v46
	v_mul_f32_e32 v79, v7, v46
	v_fmac_f32_e32 v76, v16, v96
	v_fmac_f32_e32 v77, v16, v97
	v_fmac_f32_e32 v78, v16, v98
	v_fmac_f32_e32 v79, v16, v99
	global_store_dwordx4 v[86:87], v[76:79], off nt
	v_lshl_add_u64 v[86:87], v[86:87], 0, s[42:43]
	s_waitcnt vmcnt(31)
	v_mul_f32_e32 v80, v4, v47
	v_mul_f32_e32 v81, v5, v47
	v_mul_f32_e32 v82, v6, v47
	v_mul_f32_e32 v83, v7, v47
	v_fmac_f32_e32 v80, v16, v100
	v_fmac_f32_e32 v81, v16, v101
	v_fmac_f32_e32 v82, v16, v102
	v_fmac_f32_e32 v83, v16, v103
	global_store_dwordx4 v[86:87], v[80:83], off nt
	v_lshl_add_u64 v[86:87], v[86:87], 0, s[42:43]
	s_waitcnt vmcnt(31)
	v_mul_f32_e32 v76, v4, v48
	v_mul_f32_e32 v77, v5, v48
	v_mul_f32_e32 v78, v6, v48
	v_mul_f32_e32 v79, v7, v48
	v_fmac_f32_e32 v76, v16, v104
	v_fmac_f32_e32 v77, v16, v105
	v_fmac_f32_e32 v78, v16, v106
	v_fmac_f32_e32 v79, v16, v107
	global_store_dwordx4 v[86:87], v[76:79], off nt
	v_lshl_add_u64 v[86:87], v[86:87], 0, s[42:43]
	s_waitcnt vmcnt(31)
	v_mul_f32_e32 v80, v4, v49
	v_mul_f32_e32 v81, v5, v49
	v_mul_f32_e32 v82, v6, v49
	v_mul_f32_e32 v83, v7, v49
	v_fmac_f32_e32 v80, v16, v108
	v_fmac_f32_e32 v81, v16, v109
	v_fmac_f32_e32 v82, v16, v110
	v_fmac_f32_e32 v83, v16, v111
	global_store_dwordx4 v[86:87], v[80:83], off nt
	v_lshl_add_u64 v[86:87], v[86:87], 0, s[42:43]
	s_waitcnt vmcnt(31)
	v_mul_f32_e32 v76, v4, v50
	v_mul_f32_e32 v77, v5, v50
	v_mul_f32_e32 v78, v6, v50
	v_mul_f32_e32 v79, v7, v50
	v_fmac_f32_e32 v76, v16, v112
	v_fmac_f32_e32 v77, v16, v113
	v_fmac_f32_e32 v78, v16, v114
	v_fmac_f32_e32 v79, v16, v115
	global_store_dwordx4 v[86:87], v[76:79], off nt
	v_lshl_add_u64 v[86:87], v[86:87], 0, s[42:43]
	s_waitcnt vmcnt(31)
	v_mul_f32_e32 v80, v4, v51
	v_mul_f32_e32 v81, v5, v51
	v_mul_f32_e32 v82, v6, v51
	v_mul_f32_e32 v83, v7, v51
	v_fmac_f32_e32 v80, v16, v116
	v_fmac_f32_e32 v81, v16, v117
	v_fmac_f32_e32 v82, v16, v118
	v_fmac_f32_e32 v83, v16, v119
	global_store_dwordx4 v[86:87], v[80:83], off nt
	v_lshl_add_u64 v[86:87], v[86:87], 0, s[42:43]
	s_waitcnt vmcnt(31)
	v_mul_f32_e32 v76, v4, v52
	v_mul_f32_e32 v77, v5, v52
	v_mul_f32_e32 v78, v6, v52
	v_mul_f32_e32 v79, v7, v52
	v_fmac_f32_e32 v76, v16, v120
	v_fmac_f32_e32 v77, v16, v121
	v_fmac_f32_e32 v78, v16, v122
	v_fmac_f32_e32 v79, v16, v123
	global_store_dwordx4 v[86:87], v[76:79], off nt
	v_lshl_add_u64 v[86:87], v[86:87], 0, s[42:43]
	s_waitcnt vmcnt(31)
	v_mul_f32_e32 v80, v4, v53
	v_mul_f32_e32 v81, v5, v53
	v_mul_f32_e32 v82, v6, v53
	v_mul_f32_e32 v83, v7, v53
	v_fmac_f32_e32 v80, v16, v124
	v_fmac_f32_e32 v81, v16, v125
	v_fmac_f32_e32 v82, v16, v126
	v_fmac_f32_e32 v83, v16, v127
	global_store_dwordx4 v[86:87], v[80:83], off nt
	v_lshl_add_u64 v[86:87], v[86:87], 0, s[42:43]
	s_waitcnt vmcnt(31)
	v_mul_f32_e32 v76, v4, v54
	v_mul_f32_e32 v77, v5, v54
	v_mul_f32_e32 v78, v6, v54
	v_mul_f32_e32 v79, v7, v54
	v_fmac_f32_e32 v76, v16, v128
	v_fmac_f32_e32 v77, v16, v129
	v_fmac_f32_e32 v78, v16, v130
	v_fmac_f32_e32 v79, v16, v131
	global_store_dwordx4 v[86:87], v[76:79], off nt
	v_lshl_add_u64 v[86:87], v[86:87], 0, s[42:43]
	s_waitcnt vmcnt(31)
	v_mul_f32_e32 v80, v4, v55
	v_mul_f32_e32 v81, v5, v55
	v_mul_f32_e32 v82, v6, v55
	v_mul_f32_e32 v83, v7, v55
	v_fmac_f32_e32 v80, v16, v132
	v_fmac_f32_e32 v81, v16, v133
	v_fmac_f32_e32 v82, v16, v134
	v_fmac_f32_e32 v83, v16, v135
	global_store_dwordx4 v[86:87], v[80:83], off nt
	v_lshl_add_u64 v[86:87], v[86:87], 0, s[42:43]
	s_waitcnt vmcnt(31)
	v_mul_f32_e32 v76, v4, v56
	v_mul_f32_e32 v77, v5, v56
	v_mul_f32_e32 v78, v6, v56
	v_mul_f32_e32 v79, v7, v56
	v_fmac_f32_e32 v76, v16, v136
	v_fmac_f32_e32 v77, v16, v137
	v_fmac_f32_e32 v78, v16, v138
	v_fmac_f32_e32 v79, v16, v139
	global_store_dwordx4 v[86:87], v[76:79], off nt
	v_lshl_add_u64 v[86:87], v[86:87], 0, s[42:43]
	s_waitcnt vmcnt(31)
	v_mul_f32_e32 v80, v4, v57
	v_mul_f32_e32 v81, v5, v57
	v_mul_f32_e32 v82, v6, v57
	v_mul_f32_e32 v83, v7, v57
	v_fmac_f32_e32 v80, v16, v140
	v_fmac_f32_e32 v81, v16, v141
	v_fmac_f32_e32 v82, v16, v142
	v_fmac_f32_e32 v83, v16, v143
	global_store_dwordx4 v[86:87], v[80:83], off nt
	v_lshl_add_u64 v[86:87], v[86:87], 0, s[42:43]
	s_waitcnt vmcnt(31)
	v_mul_f32_e32 v76, v4, v58
	v_mul_f32_e32 v77, v5, v58
	v_mul_f32_e32 v78, v6, v58
	v_mul_f32_e32 v79, v7, v58
	v_fmac_f32_e32 v76, v16, v144
	v_fmac_f32_e32 v77, v16, v145
	v_fmac_f32_e32 v78, v16, v146
	v_fmac_f32_e32 v79, v16, v147
	global_store_dwordx4 v[86:87], v[76:79], off nt
	v_lshl_add_u64 v[86:87], v[86:87], 0, s[42:43]
	s_waitcnt vmcnt(31)
	v_mul_f32_e32 v80, v4, v59
	v_mul_f32_e32 v81, v5, v59
	v_mul_f32_e32 v82, v6, v59
	v_mul_f32_e32 v83, v7, v59
	v_fmac_f32_e32 v80, v16, v152
	v_fmac_f32_e32 v81, v16, v153
	v_fmac_f32_e32 v82, v16, v154
	v_fmac_f32_e32 v83, v16, v155
	global_store_dwordx4 v[86:87], v[80:83], off nt
	v_lshl_add_u64 v[86:87], v[86:87], 0, s[42:43]
	s_waitcnt vmcnt(31)
; DI void ret_sample_item(const Params& p, LAS unsigned char* ldsb, int item) {
;     ...
;     for (int i = 0; i < 32; ++i) { const int dk = wid + 8 * i; const f32x4 s4 = __builtin_nontemporal_load((const f32x4*)(sin + (size_t)dk * 256 + dv4));
;         cr += s4 * qs[dk]; __builtin_nontemporal_store(s4 * g + v4 * ks[dk], (f32x4*)(sout + (size_t)dk * 256 + dv4)); }
	v_mul_f32_e32 v76, v4, v60
	v_mul_f32_e32 v77, v5, v60
	v_mul_f32_e32 v78, v6, v60
	v_mul_f32_e32 v79, v7, v60
	v_fmac_f32_e32 v76, v16, v156
	v_fmac_f32_e32 v77, v16, v157
	v_fmac_f32_e32 v78, v16, v158
	v_fmac_f32_e32 v79, v16, v159
	global_store_dwordx4 v[86:87], v[76:79], off nt
	v_lshl_add_u64 v[86:87], v[86:87], 0, s[42:43]
	s_waitcnt vmcnt(31)
	v_mul_f32_e32 v80, v4, v61
	v_mul_f32_e32 v81, v5, v61
	v_mul_f32_e32 v82, v6, v61
	v_mul_f32_e32 v83, v7, v61
	v_fmac_f32_e32 v80, v16, v160
	v_fmac_f32_e32 v81, v16, v161
	v_fmac_f32_e32 v82, v16, v162
	v_fmac_f32_e32 v83, v16, v163
	global_store_dwordx4 v[86:87], v[80:83], off nt
	v_lshl_add_u64 v[86:87], v[86:87], 0, s[42:43]
	s_waitcnt vmcnt(31)
	v_mul_f32_e32 v76, v4, v62
	v_mul_f32_e32 v77, v5, v62
	v_mul_f32_e32 v78, v6, v62
	v_mul_f32_e32 v79, v7, v62
	v_fmac_f32_e32 v76, v16, v164
	v_fmac_f32_e32 v77, v16, v165
	v_fmac_f32_e32 v78, v16, v166
	v_fmac_f32_e32 v79, v16, v167
	global_store_dwordx4 v[86:87], v[76:79], off nt
	v_lshl_add_u64 v[86:87], v[86:87], 0, s[42:43]
	s_waitcnt vmcnt(31)
	v_mul_f32_e32 v80, v4, v63
	v_mul_f32_e32 v81, v5, v63
	v_mul_f32_e32 v82, v6, v63
	v_mul_f32_e32 v83, v7, v63
	v_fmac_f32_e32 v80, v16, v168
	v_fmac_f32_e32 v81, v16, v169
	v_fmac_f32_e32 v82, v16, v170
	v_fmac_f32_e32 v83, v16, v171
	global_store_dwordx4 v[86:87], v[80:83], off nt
	v_lshl_add_u64 v[86:87], v[86:87], 0, s[42:43]
	s_waitcnt vmcnt(31)
	v_mul_f32_e32 v76, v4, v64
	v_mul_f32_e32 v77, v5, v64
	v_mul_f32_e32 v78, v6, v64
	v_mul_f32_e32 v79, v7, v64
	v_fmac_f32_e32 v76, v16, v172
	v_fmac_f32_e32 v77, v16, v173
	v_fmac_f32_e32 v78, v16, v174
	v_fmac_f32_e32 v79, v16, v175
	global_store_dwordx4 v[86:87], v[76:79], off nt
	v_lshl_add_u64 v[86:87], v[86:87], 0, s[42:43]
	s_waitcnt vmcnt(31)
	v_mul_f32_e32 v80, v4, v65
	v_mul_f32_e32 v81, v5, v65
	v_mul_f32_e32 v82, v6, v65
	v_mul_f32_e32 v83, v7, v65
	v_fmac_f32_e32 v80, v16, v176
	v_fmac_f32_e32 v81, v16, v177
	v_fmac_f32_e32 v82, v16, v178
	v_fmac_f32_e32 v83, v16, v179
	global_store_dwordx4 v[86:87], v[80:83], off nt
	v_lshl_add_u64 v[86:87], v[86:87], 0, s[42:43]
	s_waitcnt vmcnt(31)
	v_mul_f32_e32 v76, v4, v66
	v_mul_f32_e32 v77, v5, v66
	v_mul_f32_e32 v78, v6, v66
	v_mul_f32_e32 v79, v7, v66
	v_fmac_f32_e32 v76, v16, v180
	v_fmac_f32_e32 v77, v16, v181
	v_fmac_f32_e32 v78, v16, v182
	v_fmac_f32_e32 v79, v16, v183
	global_store_dwordx4 v[86:87], v[76:79], off nt
	v_lshl_add_u64 v[86:87], v[86:87], 0, s[42:43]
	s_waitcnt vmcnt(31)
	v_mul_f32_e32 v80, v4, v67
	v_mul_f32_e32 v81, v5, v67
	v_mul_f32_e32 v82, v6, v67
	v_mul_f32_e32 v83, v7, v67
	v_fmac_f32_e32 v80, v16, v184
	v_fmac_f32_e32 v81, v16, v185
	v_fmac_f32_e32 v82, v16, v186
	v_fmac_f32_e32 v83, v16, v187
	global_store_dwordx4 v[86:87], v[80:83], off nt
	v_lshl_add_u64 v[86:87], v[86:87], 0, s[42:43]
	s_waitcnt vmcnt(31)
	v_mul_f32_e32 v76, v4, v68
	v_mul_f32_e32 v77, v5, v68
	v_mul_f32_e32 v78, v6, v68
	v_mul_f32_e32 v79, v7, v68
	v_fmac_f32_e32 v76, v16, v188
	v_fmac_f32_e32 v77, v16, v189
	v_fmac_f32_e32 v78, v16, v190
	v_fmac_f32_e32 v79, v16, v191
	global_store_dwordx4 v[86:87], v[76:79], off nt
	v_lshl_add_u64 v[86:87], v[86:87], 0, s[42:43]
	s_waitcnt vmcnt(31)
	v_mul_f32_e32 v80, v4, v69
	v_mul_f32_e32 v81, v5, v69
	v_mul_f32_e32 v82, v6, v69
	v_mul_f32_e32 v83, v7, v69
	v_fmac_f32_e32 v80, v16, v192
	v_fmac_f32_e32 v81, v16, v193
	v_fmac_f32_e32 v82, v16, v194
	v_fmac_f32_e32 v83, v16, v195
	global_store_dwordx4 v[86:87], v[80:83], off nt
	v_lshl_add_u64 v[86:87], v[86:87], 0, s[42:43]
	s_waitcnt vmcnt(31)
	v_mul_f32_e32 v76, v4, v70
	v_mul_f32_e32 v77, v5, v70
	v_mul_f32_e32 v78, v6, v70
	v_mul_f32_e32 v79, v7, v70
	v_fmac_f32_e32 v76, v16, v196
	v_fmac_f32_e32 v77, v16, v197
	v_fmac_f32_e32 v78, v16, v198
	v_fmac_f32_e32 v79, v16, v199
	global_store_dwordx4 v[86:87], v[76:79], off nt
	v_lshl_add_u64 v[86:87], v[86:87], 0, s[42:43]
	s_waitcnt vmcnt(31)
	v_mul_f32_e32 v80, v4, v71
	v_mul_f32_e32 v81, v5, v71
	v_mul_f32_e32 v82, v6, v71
	v_mul_f32_e32 v83, v7, v71
	v_fmac_f32_e32 v80, v16, v200
	v_fmac_f32_e32 v81, v16, v201
	v_fmac_f32_e32 v82, v16, v202
	v_fmac_f32_e32 v83, v16, v203
	global_store_dwordx4 v[86:87], v[80:83], off nt
	v_lshl_add_u64 v[86:87], v[86:87], 0, s[42:43]
	s_waitcnt vmcnt(31)
	v_mul_f32_e32 v76, v4, v72
	v_mul_f32_e32 v77, v5, v72
	v_mul_f32_e32 v78, v6, v72
	v_mul_f32_e32 v79, v7, v72
	v_fmac_f32_e32 v76, v16, v204
	v_fmac_f32_e32 v77, v16, v205
	v_fmac_f32_e32 v78, v16, v206
	v_fmac_f32_e32 v79, v16, v207
	global_store_dwordx4 v[86:87], v[76:79], off nt
	v_lshl_add_u64 v[86:87], v[86:87], 0, s[42:43]
	s_waitcnt vmcnt(31)
	v_mul_f32_e32 v80, v4, v73
	v_mul_f32_e32 v81, v5, v73
	v_mul_f32_e32 v82, v6, v73
	v_mul_f32_e32 v83, v7, v73
	v_fmac_f32_e32 v80, v16, v208
	v_fmac_f32_e32 v81, v16, v209
	v_fmac_f32_e32 v82, v16, v210
	v_fmac_f32_e32 v83, v16, v211
	global_store_dwordx4 v[86:87], v[80:83], off nt
	v_lshl_add_u64 v[86:87], v[86:87], 0, s[42:43]
	s_waitcnt vmcnt(31)
	v_mul_f32_e32 v76, v4, v74
	v_mul_f32_e32 v77, v5, v74
	v_mul_f32_e32 v78, v6, v74
	v_mul_f32_e32 v79, v7, v74
	v_fmac_f32_e32 v76, v16, v212
	v_fmac_f32_e32 v77, v16, v213
	v_fmac_f32_e32 v78, v16, v214
	v_fmac_f32_e32 v79, v16, v215
	global_store_dwordx4 v[86:87], v[76:79], off nt
	v_lshl_add_u64 v[86:87], v[86:87], 0, s[42:43]
	s_waitcnt vmcnt(31)
; #define LAS __attribute__((address_space(3)))
; DI void ret_sample_item(const Params& p, LAS unsigned char* ldsb, int item) {
;     ...
;     for (int i = 0; i < 32; ++i) { const int dk = wid + 8 * i; const f32x4 s4 = __builtin_nontemporal_load((const f32x4*)(sin + (size_t)dk * 256 + dv4));
;         cr += s4 * qs[dk]; __builtin_nontemporal_store(s4 * g + v4 * ks[dk], (f32x4*)(sout + (size_t)dk * 256 + dv4)); }
;     *(LAS f32x4*)(red + wid * 256 + dv4) = cr;
;     __syncthreads();
;     float o = 0.f;
;     if (tid < 256) { float cs = 0.f;
; #pragma unroll
;         for (int w = 0; w < 8; ++w) cs += red[w * 256 + tid];
;         o = score * vs[tid] + cs * g; }
;     const float ssw = wave_sum(o * o);
;     if (lane == 0) misc[wid] = ssw;
;     __syncthreads();
;     if (tid < 256) { const float ss = misc[0] + misc[1] + misc[2] + misc[3]; const float rstd = rsqrtf(ss * (1.0f / 256.0f) + EPS);
	v_mul_f32_e32 v80, v4, v75
	v_mul_f32_e32 v81, v5, v75
	v_mul_f32_e32 v82, v6, v75
	v_mul_f32_e32 v83, v7, v75
	v_fmac_f32_e32 v80, v16, v216
	v_fmac_f32_e32 v81, v16, v217
	v_fmac_f32_e32 v82, v16, v218
	v_fmac_f32_e32 v83, v16, v219
	global_store_dwordx4 v[86:87], v[80:83], off nt
	ds_read2_b32 v[44:45], v15 offset0:0 offset1:8
	ds_read2_b32 v[46:47], v15 offset0:16 offset1:24
	ds_read2_b32 v[48:49], v15 offset0:32 offset1:40
	ds_read2_b32 v[50:51], v15 offset0:48 offset1:56
	ds_read2_b32 v[52:53], v15 offset0:64 offset1:72
	ds_read2_b32 v[54:55], v15 offset0:80 offset1:88
	ds_read2_b32 v[56:57], v15 offset0:96 offset1:104
	ds_read2_b32 v[58:59], v15 offset0:112 offset1:120
	ds_read2_b32 v[60:61], v15 offset0:128 offset1:136
	ds_read2_b32 v[62:63], v15 offset0:144 offset1:152
	ds_read2_b32 v[64:65], v15 offset0:160 offset1:168
	ds_read2_b32 v[66:67], v15 offset0:176 offset1:184
	ds_read2_b32 v[68:69], v15 offset0:192 offset1:200
	ds_read2_b32 v[70:71], v15 offset0:208 offset1:216
	ds_read2_b32 v[72:73], v15 offset0:224 offset1:232
	ds_read2_b32 v[74:75], v15 offset0:240 offset1:248
	s_waitcnt lgkmcnt(0)
	v_fmac_f32_e32 v0, v88, v44
	v_fmac_f32_e32 v1, v89, v44
	v_fmac_f32_e32 v2, v90, v44
	v_fmac_f32_e32 v3, v91, v44
	v_fmac_f32_e32 v0, v92, v45
	v_fmac_f32_e32 v1, v93, v45
	v_fmac_f32_e32 v2, v94, v45
	v_fmac_f32_e32 v3, v95, v45
	v_fmac_f32_e32 v0, v96, v46
	v_fmac_f32_e32 v1, v97, v46
	v_fmac_f32_e32 v2, v98, v46
	v_fmac_f32_e32 v3, v99, v46
	v_fmac_f32_e32 v0, v100, v47
	v_fmac_f32_e32 v1, v101, v47
	v_fmac_f32_e32 v2, v102, v47
	v_fmac_f32_e32 v3, v103, v47
	v_fmac_f32_e32 v0, v104, v48
	v_fmac_f32_e32 v1, v105, v48
	v_fmac_f32_e32 v2, v106, v48
	v_fmac_f32_e32 v3, v107, v48
	v_fmac_f32_e32 v0, v108, v49
	v_fmac_f32_e32 v1, v109, v49
	v_fmac_f32_e32 v2, v110, v49
	v_fmac_f32_e32 v3, v111, v49
	v_fmac_f32_e32 v0, v112, v50
	v_fmac_f32_e32 v1, v113, v50
	v_fmac_f32_e32 v2, v114, v50
	v_fmac_f32_e32 v3, v115, v50
	v_fmac_f32_e32 v0, v116, v51
	v_fmac_f32_e32 v1, v117, v51
	v_fmac_f32_e32 v2, v118, v51
	v_fmac_f32_e32 v3, v119, v51
	v_fmac_f32_e32 v0, v120, v52
	v_fmac_f32_e32 v1, v121, v52
	v_fmac_f32_e32 v2, v122, v52
	v_fmac_f32_e32 v3, v123, v52
	v_fmac_f32_e32 v0, v124, v53
	v_fmac_f32_e32 v1, v125, v53
	v_fmac_f32_e32 v2, v126, v53
	v_fmac_f32_e32 v3, v127, v53
	v_fmac_f32_e32 v0, v128, v54
	v_fmac_f32_e32 v1, v129, v54
	v_fmac_f32_e32 v2, v130, v54
	v_fmac_f32_e32 v3, v131, v54
	v_fmac_f32_e32 v0, v132, v55
	v_fmac_f32_e32 v1, v133, v55
	v_fmac_f32_e32 v2, v134, v55
	v_fmac_f32_e32 v3, v135, v55
	v_fmac_f32_e32 v0, v136, v56
	v_fmac_f32_e32 v1, v137, v56
	v_fmac_f32_e32 v2, v138, v56
	v_fmac_f32_e32 v3, v139, v56
	v_fmac_f32_e32 v0, v140, v57
	v_fmac_f32_e32 v1, v141, v57
	v_fmac_f32_e32 v2, v142, v57
	v_fmac_f32_e32 v3, v143, v57
	v_fmac_f32_e32 v0, v144, v58
	v_fmac_f32_e32 v1, v145, v58
	v_fmac_f32_e32 v2, v146, v58
	v_fmac_f32_e32 v3, v147, v58
	v_fmac_f32_e32 v0, v152, v59
	v_fmac_f32_e32 v1, v153, v59
	v_fmac_f32_e32 v2, v154, v59
	v_fmac_f32_e32 v3, v155, v59
	v_fmac_f32_e32 v0, v156, v60
	v_fmac_f32_e32 v1, v157, v60
	v_fmac_f32_e32 v2, v158, v60
	v_fmac_f32_e32 v3, v159, v60
	v_fmac_f32_e32 v0, v160, v61
	v_fmac_f32_e32 v1, v161, v61
	v_fmac_f32_e32 v2, v162, v61
	v_fmac_f32_e32 v3, v163, v61
	v_fmac_f32_e32 v0, v164, v62
	v_fmac_f32_e32 v1, v165, v62
	v_fmac_f32_e32 v2, v166, v62
	v_fmac_f32_e32 v3, v167, v62
	v_fmac_f32_e32 v0, v168, v63
	v_fmac_f32_e32 v1, v169, v63
	v_fmac_f32_e32 v2, v170, v63
	v_fmac_f32_e32 v3, v171, v63
	v_fmac_f32_e32 v0, v172, v64
	v_fmac_f32_e32 v1, v173, v64
	v_fmac_f32_e32 v2, v174, v64
	v_fmac_f32_e32 v3, v175, v64
	v_fmac_f32_e32 v0, v176, v65
	v_fmac_f32_e32 v1, v177, v65
	v_fmac_f32_e32 v2, v178, v65
	v_fmac_f32_e32 v3, v179, v65
	v_fmac_f32_e32 v0, v180, v66
	v_fmac_f32_e32 v1, v181, v66
	v_fmac_f32_e32 v2, v182, v66
	v_fmac_f32_e32 v3, v183, v66
	v_fmac_f32_e32 v0, v184, v67
	v_fmac_f32_e32 v1, v185, v67
	v_fmac_f32_e32 v2, v186, v67
	v_fmac_f32_e32 v3, v187, v67
	v_fmac_f32_e32 v0, v188, v68
	v_fmac_f32_e32 v1, v189, v68
	v_fmac_f32_e32 v2, v190, v68
	v_fmac_f32_e32 v3, v191, v68
	v_fmac_f32_e32 v0, v192, v69
	v_fmac_f32_e32 v1, v193, v69
	v_fmac_f32_e32 v2, v194, v69
	v_fmac_f32_e32 v3, v195, v69
	v_fmac_f32_e32 v0, v196, v70
	v_fmac_f32_e32 v1, v197, v70
	v_fmac_f32_e32 v2, v198, v70
	v_fmac_f32_e32 v3, v199, v70
	v_fmac_f32_e32 v0, v200, v71
	v_fmac_f32_e32 v1, v201, v71
	v_fmac_f32_e32 v2, v202, v71
	v_fmac_f32_e32 v3, v203, v71
	v_fmac_f32_e32 v0, v204, v72
	v_fmac_f32_e32 v1, v205, v72
	v_fmac_f32_e32 v2, v206, v72
	v_fmac_f32_e32 v3, v207, v72
	v_fmac_f32_e32 v0, v208, v73
	v_fmac_f32_e32 v1, v209, v73
	v_fmac_f32_e32 v2, v210, v73
	v_fmac_f32_e32 v3, v211, v73
	v_fmac_f32_e32 v0, v212, v74
	v_fmac_f32_e32 v1, v213, v74
	v_fmac_f32_e32 v2, v214, v74
	v_fmac_f32_e32 v3, v215, v74
	v_fmac_f32_e32 v0, v216, v75
	v_fmac_f32_e32 v1, v217, v75
	v_fmac_f32_e32 v2, v218, v75
	v_fmac_f32_e32 v3, v219, v75
	v_xor_b32_e32 v4, 32, v24
	v_cmp_lt_i32_e32 vcc, v4, v25
	v_add_f32_e32 v7, v41, v42
	s_nop 0
	v_cndmask_b32_e32 v4, v24, v4, vcc
	v_lshlrev_b32_e32 v5, 2, v4
	ds_bpermute_b32 v9, v5, v7
	v_lshl_add_u32 v4, v14, 10, 0
	v_lshl_add_u32 v6, v35, 4, v4
	ds_write_b128 v6, v[0:3] offset:3072
	v_mov_b32_e32 v0, 0
	s_waitcnt lgkmcnt(0)
	s_barrier
	s_and_saveexec_b64 s[42:43], s[6:7]
	s_cbranch_execz .LBB0_1949
	ds_read2st64_b32 v[0:1], v34 offset0:8 offset1:12
	ds_read2st64_b32 v[2:3], v34 offset0:16 offset1:20
	ds_read2st64_b32 v[10:11], v34 offset0:24 offset1:28
	ds_read2st64_b32 v[18:19], v34 offset0:32 offset1:36
	ds_read_b32 v8, v34 offset:10240
	s_waitcnt lgkmcnt(4)
	v_add_f32_e32 v1, 0, v1
	s_waitcnt lgkmcnt(3)
	v_add_f32_e32 v1, v1, v2
	v_add_f32_e32 v1, v1, v3
	s_waitcnt lgkmcnt(2)
	v_add_f32_e32 v1, v1, v10
	v_add_f32_e32 v1, v1, v11
	s_waitcnt lgkmcnt(1)
	v_add_f32_e32 v1, v1, v18
	v_add_f32_e32 v6, v1, v19
	s_waitcnt lgkmcnt(0)
	v_pk_add_f32 v[2:3], v[6:7], v[8:9]
	v_mov_b32_e32 v17, v0
	v_pk_mul_f32 v[0:1], v[16:17], v[2:3]
	s_nop 0
	v_add_f32_e32 v0, v0, v1

; DI void unpack8(const u32x4 w, float (&f)[8]) { f[0] = bflo(w.x); f[1] = bfhi(w.x); f[2] = bflo(w.y); f[3] = bfhi(w.y); f[4] = bflo(w.z); f[5] = bfhi(w.z); f[6] = bflo(w.w); f[7] = bfhi(w.w); }
; DI u32x4 pack8(const float (&f)[8]) { u32x4 w; w.x = pk2(f[0], f[1]); w.y = pk2(f[2], f[3]); w.z = pk2(f[4], f[5]); w.w = pk2(f[6], f[7]); return w; }
; DI float ret_log2g(int h) { return log2f(1.0f - exp2f(-5.0f - (float)h)); }
; DI void phase8(const Params& p, LAS unsigned char* lds) {
;     ...
;     for (int it = blockIdx.x * NTHREADS + tid; it < 16 * 8192; it += G * NTHREADS) {
;         const int bh = it >> 13, e = (it & 8191) * 8, dv = e >> 8, dk0 = e & 255;
;         const float g256 = exp2f(256.0f * ret_log2g(bh & 3));
;         float s[8];
; #pragma unroll
;         for (int k = 0; k < 8; ++k) s[k] = 0.f;
; #pragma unroll
;         for (int c = 0; c < 16; ++c) {
;             const size_t u = (size_t)(bh * 16 + c);
;             float kv[8]; unpack8(__builtin_nontemporal_load((const u32x4*)(KVC + u * 65536 + e)), kv);
;             *(u32x4*)(BSV + (u * 256 + dv) * 512 + dk0) = pack8(s);
; #pragma unroll
;             for (int k = 0; k < 8; ++k) s[k] = g256 * s[k] + kv[k];
;         }
;         float* o = p.out + O_RETP + (size_t)bh * 65536 + (size_t)dk0 * 256 + dv;
; #pragma unroll
;         for (int k = 0; k < 8; ++k) __builtin_nontemporal_store(s[k], o + (size_t)k * 256);
.LBB0_1953:
	v_add_u32_e32 v32, s80, v148
	s_mov_b32 s0, 0x20000
	v_cmp_gt_i32_e32 vcc, s0, v32
	s_and_saveexec_b64 s[0:1], vcc
	s_cbranch_execz .LBB0_1956
	v_ashrrev_i32_e32 v13, 13, v32
	v_and_b32_e32 v14, 0x1fff, v32
	v_lshrrev_b32_e32 v15, 5, v14
	v_and_b32_e32 v14, 31, v14
	v_lshlrev_b32_e32 v9, 21, v13
	v_lshl_add_u32 v9, v15, 9, v9
	v_lshl_add_u32 v9, v14, 4, v9
	v_lshlrev_b32_e32 v10, 22, v13
	v_lshl_add_u32 v10, v15, 10, v10
	v_lshl_add_u32 v10, v14, 4, v10
	v_lshlrev_b32_e32 v11, 18, v13
	v_lshl_add_u32 v11, v14, 13, v11
	v_lshl_add_u32 v11, v15, 2, v11
	v_add_u32_e32 v12, 0x1000, v11
	s_add_u32 s12, s26, 0x1f400000
	s_addc_u32 s13, s27, 0
	global_load_dwordx4 v[24:27], v9, s[12:13] nt
	s_add_u32 s12, s12, 0x20000
	s_addc_u32 s13, s13, 0
	global_load_dwordx4 v[28:31], v9, s[12:13] nt
	s_add_u32 s12, s12, 0x20000
	s_addc_u32 s13, s13, 0
	global_load_dwordx4 v[32:35], v9, s[12:13] nt
	s_add_u32 s12, s12, 0x20000
	s_addc_u32 s13, s13, 0
	global_load_dwordx4 v[36:39], v9, s[12:13] nt
	s_add_u32 s12, s12, 0x20000
	s_addc_u32 s13, s13, 0
	global_load_dwordx4 v[40:43], v9, s[12:13] nt
	s_add_u32 s12, s12, 0x20000
	s_addc_u32 s13, s13, 0
	global_load_dwordx4 v[44:47], v9, s[12:13] nt
	s_add_u32 s12, s12, 0x20000
	s_addc_u32 s13, s13, 0
	global_load_dwordx4 v[48:51], v9, s[12:13] nt
	s_add_u32 s12, s12, 0x20000
	s_addc_u32 s13, s13, 0
	global_load_dwordx4 v[52:55], v9, s[12:13] nt
	s_add_u32 s12, s12, 0x20000
	s_addc_u32 s13, s13, 0
	global_load_dwordx4 v[56:59], v9, s[12:13] nt
	s_add_u32 s12, s12, 0x20000
	s_addc_u32 s13, s13, 0
	global_load_dwordx4 v[60:63], v9, s[12:13] nt
	s_add_u32 s12, s12, 0x20000
	s_addc_u32 s13, s13, 0
	global_load_dwordx4 v[64:67], v9, s[12:13] nt
	s_add_u32 s12, s12, 0x20000
	s_addc_u32 s13, s13, 0
	global_load_dwordx4 v[68:71], v9, s[12:13] nt
	s_add_u32 s12, s12, 0x20000
	s_addc_u32 s13, s13, 0
	global_load_dwordx4 v[72:75], v9, s[12:13] nt
	s_add_u32 s12, s12, 0x20000
	s_addc_u32 s13, s13, 0
	global_load_dwordx4 v[76:79], v9, s[12:13] nt
	s_add_u32 s12, s12, 0x20000
	s_addc_u32 s13, s13, 0
	global_load_dwordx4 v[80:83], v9, s[12:13] nt
	s_add_u32 s12, s12, 0x20000
	s_addc_u32 s13, s13, 0
	global_load_dwordx4 v[84:87], v9, s[12:13] nt
	v_and_b32_e32 v13, 3, v13
	v_cvt_f32_ubyte0_e32 v13, v13
	v_sub_f32_e32 v13, 0xc0a00000, v13
	v_exp_f32_e32 v13, v13
	s_nop 0
	v_sub_f32_e32 v13, 1.0, v13
	v_log_f32_e32 v13, v13
	s_nop 0
	v_mul_f32_e32 v13, 0x43800000, v13
	v_exp_f32_e32 v8, v13
	s_add_u32 s14, s26, 0x27400000
	s_addc_u32 s15, s27, 0
	s_add_u32 s6, s24, 0x82c4000
	s_addc_u32 s7, s25, 0
	v_mov_b32_e32 v0, 0
	v_mov_b32_e32 v1, 0
	v_mov_b32_e32 v2, 0
	v_mov_b32_e32 v3, 0
	v_mov_b32_e32 v4, 0
	v_mov_b32_e32 v5, 0
	v_mov_b32_e32 v6, 0
	v_mov_b32_e32 v7, 0
	v_cvt_pk_bf16_f32 v88, v0, v1
	v_cvt_pk_bf16_f32 v89, v2, v3
	v_cvt_pk_bf16_f32 v90, v4, v5
	v_cvt_pk_bf16_f32 v91, v6, v7
	global_store_dwordx4 v10, v[88:91], s[14:15]
	s_add_u32 s14, s14, 0x40000
	s_addc_u32 s15, s15, 0
	s_waitcnt vmcnt(16)
	v_lshlrev_b32_e32 v16, 16, v24
	v_and_b32_e32 v17, 0xffff0000, v24
	v_lshlrev_b32_e32 v18, 16, v25
	v_and_b32_e32 v19, 0xffff0000, v25
	v_lshlrev_b32_e32 v20, 16, v26
	v_and_b32_e32 v21, 0xffff0000, v26
	v_lshlrev_b32_e32 v22, 16, v27
	v_and_b32_e32 v23, 0xffff0000, v27
	v_fma_f32 v0, v8, v0, v16
	v_fma_f32 v1, v8, v1, v17
	v_fma_f32 v2, v8, v2, v18
	v_fma_f32 v3, v8, v3, v19
	v_fma_f32 v4, v8, v4, v20
	v_fma_f32 v5, v8, v5, v21
	v_fma_f32 v6, v8, v6, v22
	v_fma_f32 v7, v8, v7, v23
	v_cvt_pk_bf16_f32 v24, v0, v1
	v_cvt_pk_bf16_f32 v25, v2, v3
	v_cvt_pk_bf16_f32 v26, v4, v5
	v_cvt_pk_bf16_f32 v27, v6, v7
	global_store_dwordx4 v10, v[24:27], s[14:15]
	s_add_u32 s14, s14, 0x40000
	s_addc_u32 s15, s15, 0
	s_waitcnt vmcnt(16)
	v_lshlrev_b32_e32 v16, 16, v28
	v_and_b32_e32 v17, 0xffff0000, v28
	v_lshlrev_b32_e32 v18, 16, v29
	v_and_b32_e32 v19, 0xffff0000, v29
	v_lshlrev_b32_e32 v20, 16, v30
	v_and_b32_e32 v21, 0xffff0000, v30
	v_lshlrev_b32_e32 v22, 16, v31
	v_and_b32_e32 v23, 0xffff0000, v31
	v_fma_f32 v0, v8, v0, v16
	v_fma_f32 v1, v8, v1, v17
	v_fma_f32 v2, v8, v2, v18
	v_fma_f32 v3, v8, v3, v19
	v_fma_f32 v4, v8, v4, v20
	v_fma_f32 v5, v8, v5, v21
	v_fma_f32 v6, v8, v6, v22
	v_fma_f32 v7, v8, v7, v23
	v_cvt_pk_bf16_f32 v28, v0, v1
	v_cvt_pk_bf16_f32 v29, v2, v3
	v_cvt_pk_bf16_f32 v30, v4, v5
	v_cvt_pk_bf16_f32 v31, v6, v7
	global_store_dwordx4 v10, v[28:31], s[14:15]
	s_add_u32 s14, s14, 0x40000
	s_addc_u32 s15, s15, 0
	s_waitcnt vmcnt(16)
	v_lshlrev_b32_e32 v16, 16, v32
	v_and_b32_e32 v17, 0xffff0000, v32
	v_lshlrev_b32_e32 v18, 16, v33
	v_and_b32_e32 v19, 0xffff0000, v33
	v_lshlrev_b32_e32 v20, 16, v34
	v_and_b32_e32 v21, 0xffff0000, v34
	v_lshlrev_b32_e32 v22, 16, v35
	v_and_b32_e32 v23, 0xffff0000, v35
	v_fma_f32 v0, v8, v0, v16
	v_fma_f32 v1, v8, v1, v17
	v_fma_f32 v2, v8, v2, v18
	v_fma_f32 v3, v8, v3, v19
	v_fma_f32 v4, v8, v4, v20
	v_fma_f32 v5, v8, v5, v21
	v_fma_f32 v6, v8, v6, v22
	v_fma_f32 v7, v8, v7, v23
	v_cvt_pk_bf16_f32 v32, v0, v1
	v_cvt_pk_bf16_f32 v33, v2, v3
	v_cvt_pk_bf16_f32 v34, v4, v5
	v_cvt_pk_bf16_f32 v35, v6, v7
	global_store_dwordx4 v10, v[32:35], s[14:15]
	s_add_u32 s14, s14, 0x40000
	s_addc_u32 s15, s15, 0
	s_waitcnt vmcnt(16)
	v_lshlrev_b32_e32 v16, 16, v36
	v_and_b32_e32 v17, 0xffff0000, v36
	v_lshlrev_b32_e32 v18, 16, v37
	v_and_b32_e32 v19, 0xffff0000, v37
	v_lshlrev_b32_e32 v20, 16, v38
	v_and_b32_e32 v21, 0xffff0000, v38
	v_lshlrev_b32_e32 v22, 16, v39
	v_and_b32_e32 v23, 0xffff0000, v39
	v_fma_f32 v0, v8, v0, v16
	v_fma_f32 v1, v8, v1, v17
	v_fma_f32 v2, v8, v2, v18
	v_fma_f32 v3, v8, v3, v19
	v_fma_f32 v4, v8, v4, v20
	v_fma_f32 v5, v8, v5, v21
	v_fma_f32 v6, v8, v6, v22
	v_fma_f32 v7, v8, v7, v23
	v_cvt_pk_bf16_f32 v36, v0, v1
	v_cvt_pk_bf16_f32 v37, v2, v3
	v_cvt_pk_bf16_f32 v38, v4, v5
	v_cvt_pk_bf16_f32 v39, v6, v7
	global_store_dwordx4 v10, v[36:39], s[14:15]
	s_add_u32 s14, s14, 0x40000
	s_addc_u32 s15, s15, 0
	s_waitcnt vmcnt(16)
; DI void unpack8(const u32x4 w, float (&f)[8]) { f[0] = bflo(w.x); f[1] = bfhi(w.x); f[2] = bflo(w.y); f[3] = bfhi(w.y); f[4] = bflo(w.z); f[5] = bfhi(w.z); f[6] = bflo(w.w); f[7] = bfhi(w.w); }
; DI u32x4 pack8(const float (&f)[8]) { u32x4 w; w.x = pk2(f[0], f[1]); w.y = pk2(f[2], f[3]); w.z = pk2(f[4], f[5]); w.w = pk2(f[6], f[7]); return w; }
; DI void phase8(const Params& p, LAS unsigned char* lds) {
;     ...
;         for (int c = 0; c < 16; ++c) {
;             const size_t u = (size_t)(bh * 16 + c);
;             float kv[8]; unpack8(__builtin_nontemporal_load((const u32x4*)(KVC + u * 65536 + e)), kv);
;             *(u32x4*)(BSV + (u * 256 + dv) * 512 + dk0) = pack8(s);
; #pragma unroll
;             for (int k = 0; k < 8; ++k) s[k] = g256 * s[k] + kv[k];
;         }
	v_lshlrev_b32_e32 v16, 16, v40
	v_and_b32_e32 v17, 0xffff0000, v40
	v_lshlrev_b32_e32 v18, 16, v41
	v_and_b32_e32 v19, 0xffff0000, v41
	v_lshlrev_b32_e32 v20, 16, v42
	v_and_b32_e32 v21, 0xffff0000, v42
	v_lshlrev_b32_e32 v22, 16, v43
	v_and_b32_e32 v23, 0xffff0000, v43
	v_fma_f32 v0, v8, v0, v16
	v_fma_f32 v1, v8, v1, v17
	v_fma_f32 v2, v8, v2, v18
	v_fma_f32 v3, v8, v3, v19
	v_fma_f32 v4, v8, v4, v20
	v_fma_f32 v5, v8, v5, v21
	v_fma_f32 v6, v8, v6, v22
	v_fma_f32 v7, v8, v7, v23
	v_cvt_pk_bf16_f32 v40, v0, v1
	v_cvt_pk_bf16_f32 v41, v2, v3
	v_cvt_pk_bf16_f32 v42, v4, v5
	v_cvt_pk_bf16_f32 v43, v6, v7
	global_store_dwordx4 v10, v[40:43], s[14:15]
	s_add_u32 s14, s14, 0x40000
	s_addc_u32 s15, s15, 0
	s_waitcnt vmcnt(16)
	v_lshlrev_b32_e32 v16, 16, v44
	v_and_b32_e32 v17, 0xffff0000, v44
	v_lshlrev_b32_e32 v18, 16, v45
	v_and_b32_e32 v19, 0xffff0000, v45
	v_lshlrev_b32_e32 v20, 16, v46
	v_and_b32_e32 v21, 0xffff0000, v46
	v_lshlrev_b32_e32 v22, 16, v47
	v_and_b32_e32 v23, 0xffff0000, v47
	v_fma_f32 v0, v8, v0, v16
	v_fma_f32 v1, v8, v1, v17
	v_fma_f32 v2, v8, v2, v18
	v_fma_f32 v3, v8, v3, v19
	v_fma_f32 v4, v8, v4, v20
	v_fma_f32 v5, v8, v5, v21
	v_fma_f32 v6, v8, v6, v22
	v_fma_f32 v7, v8, v7, v23
	v_cvt_pk_bf16_f32 v44, v0, v1
	v_cvt_pk_bf16_f32 v45, v2, v3
	v_cvt_pk_bf16_f32 v46, v4, v5
	v_cvt_pk_bf16_f32 v47, v6, v7
	global_store_dwordx4 v10, v[44:47], s[14:15]
	s_add_u32 s14, s14, 0x40000
	s_addc_u32 s15, s15, 0
	s_waitcnt vmcnt(16)
	v_lshlrev_b32_e32 v16, 16, v48
	v_and_b32_e32 v17, 0xffff0000, v48
	v_lshlrev_b32_e32 v18, 16, v49
	v_and_b32_e32 v19, 0xffff0000, v49
	v_lshlrev_b32_e32 v20, 16, v50
	v_and_b32_e32 v21, 0xffff0000, v50
	v_lshlrev_b32_e32 v22, 16, v51
	v_and_b32_e32 v23, 0xffff0000, v51
	v_fma_f32 v0, v8, v0, v16
	v_fma_f32 v1, v8, v1, v17
	v_fma_f32 v2, v8, v2, v18
	v_fma_f32 v3, v8, v3, v19
	v_fma_f32 v4, v8, v4, v20
	v_fma_f32 v5, v8, v5, v21
	v_fma_f32 v6, v8, v6, v22
	v_fma_f32 v7, v8, v7, v23
	v_cvt_pk_bf16_f32 v48, v0, v1
	v_cvt_pk_bf16_f32 v49, v2, v3
	v_cvt_pk_bf16_f32 v50, v4, v5
	v_cvt_pk_bf16_f32 v51, v6, v7
	global_store_dwordx4 v10, v[48:51], s[14:15]
	s_add_u32 s14, s14, 0x40000
	s_addc_u32 s15, s15, 0
	s_waitcnt vmcnt(16)
	v_lshlrev_b32_e32 v16, 16, v52
	v_and_b32_e32 v17, 0xffff0000, v52
	v_lshlrev_b32_e32 v18, 16, v53
	v_and_b32_e32 v19, 0xffff0000, v53
	v_lshlrev_b32_e32 v20, 16, v54
	v_and_b32_e32 v21, 0xffff0000, v54
	v_lshlrev_b32_e32 v22, 16, v55
	v_and_b32_e32 v23, 0xffff0000, v55
	v_fma_f32 v0, v8, v0, v16
	v_fma_f32 v1, v8, v1, v17
	v_fma_f32 v2, v8, v2, v18
	v_fma_f32 v3, v8, v3, v19
	v_fma_f32 v4, v8, v4, v20
	v_fma_f32 v5, v8, v5, v21
	v_fma_f32 v6, v8, v6, v22
	v_fma_f32 v7, v8, v7, v23
	v_cvt_pk_bf16_f32 v52, v0, v1
	v_cvt_pk_bf16_f32 v53, v2, v3
	v_cvt_pk_bf16_f32 v54, v4, v5
	v_cvt_pk_bf16_f32 v55, v6, v7
	global_store_dwordx4 v10, v[52:55], s[14:15]
	s_add_u32 s14, s14, 0x40000
	s_addc_u32 s15, s15, 0
	s_waitcnt vmcnt(16)
	v_lshlrev_b32_e32 v16, 16, v56
	v_and_b32_e32 v17, 0xffff0000, v56
	v_lshlrev_b32_e32 v18, 16, v57
	v_and_b32_e32 v19, 0xffff0000, v57
	v_lshlrev_b32_e32 v20, 16, v58
	v_and_b32_e32 v21, 0xffff0000, v58
	v_lshlrev_b32_e32 v22, 16, v59
	v_and_b32_e32 v23, 0xffff0000, v59
	v_fma_f32 v0, v8, v0, v16
	v_fma_f32 v1, v8, v1, v17
	v_fma_f32 v2, v8, v2, v18
	v_fma_f32 v3, v8, v3, v19
	v_fma_f32 v4, v8, v4, v20
	v_fma_f32 v5, v8, v5, v21
	v_fma_f32 v6, v8, v6, v22
	v_fma_f32 v7, v8, v7, v23
	v_cvt_pk_bf16_f32 v56, v0, v1
	v_cvt_pk_bf16_f32 v57, v2, v3
	v_cvt_pk_bf16_f32 v58, v4, v5
	v_cvt_pk_bf16_f32 v59, v6, v7
	global_store_dwordx4 v10, v[56:59], s[14:15]
	s_add_u32 s14, s14, 0x40000
	s_addc_u32 s15, s15, 0
	s_waitcnt vmcnt(16)
	v_lshlrev_b32_e32 v16, 16, v60
	v_and_b32_e32 v17, 0xffff0000, v60
	v_lshlrev_b32_e32 v18, 16, v61
	v_and_b32_e32 v19, 0xffff0000, v61
	v_lshlrev_b32_e32 v20, 16, v62
	v_and_b32_e32 v21, 0xffff0000, v62
	v_lshlrev_b32_e32 v22, 16, v63
	v_and_b32_e32 v23, 0xffff0000, v63
	v_fma_f32 v0, v8, v0, v16
	v_fma_f32 v1, v8, v1, v17
	v_fma_f32 v2, v8, v2, v18
	v_fma_f32 v3, v8, v3, v19
	v_fma_f32 v4, v8, v4, v20
	v_fma_f32 v5, v8, v5, v21
	v_fma_f32 v6, v8, v6, v22
	v_fma_f32 v7, v8, v7, v23
	v_cvt_pk_bf16_f32 v60, v0, v1
	v_cvt_pk_bf16_f32 v61, v2, v3
	v_cvt_pk_bf16_f32 v62, v4, v5
	v_cvt_pk_bf16_f32 v63, v6, v7
	global_store_dwordx4 v10, v[60:63], s[14:15]
	s_add_u32 s14, s14, 0x40000
	s_addc_u32 s15, s15, 0
	s_waitcnt vmcnt(16)
; DI void unpack8(const u32x4 w, float (&f)[8]) { f[0] = bflo(w.x); f[1] = bfhi(w.x); f[2] = bflo(w.y); f[3] = bfhi(w.y); f[4] = bflo(w.z); f[5] = bfhi(w.z); f[6] = bflo(w.w); f[7] = bfhi(w.w); }
; DI u32x4 pack8(const float (&f)[8]) { u32x4 w; w.x = pk2(f[0], f[1]); w.y = pk2(f[2], f[3]); w.z = pk2(f[4], f[5]); w.w = pk2(f[6], f[7]); return w; }
; DI void phase8(const Params& p, LAS unsigned char* lds) {
;     ...
;         for (int c = 0; c < 16; ++c) {
;             const size_t u = (size_t)(bh * 16 + c);
;             float kv[8]; unpack8(__builtin_nontemporal_load((const u32x4*)(KVC + u * 65536 + e)), kv);
;             *(u32x4*)(BSV + (u * 256 + dv) * 512 + dk0) = pack8(s);
; #pragma unroll
;             for (int k = 0; k < 8; ++k) s[k] = g256 * s[k] + kv[k];
;         }
;         float* o = p.out + O_RETP + (size_t)bh * 65536 + (size_t)dk0 * 256 + dv;
; #pragma unroll
;         for (int k = 0; k < 8; ++k) __builtin_nontemporal_store(s[k], o + (size_t)k * 256);
	v_lshlrev_b32_e32 v16, 16, v64
	v_and_b32_e32 v17, 0xffff0000, v64
	v_lshlrev_b32_e32 v18, 16, v65
	v_and_b32_e32 v19, 0xffff0000, v65
	v_lshlrev_b32_e32 v20, 16, v66
	v_and_b32_e32 v21, 0xffff0000, v66
	v_lshlrev_b32_e32 v22, 16, v67
	v_and_b32_e32 v23, 0xffff0000, v67
	v_fma_f32 v0, v8, v0, v16
	v_fma_f32 v1, v8, v1, v17
	v_fma_f32 v2, v8, v2, v18
	v_fma_f32 v3, v8, v3, v19
	v_fma_f32 v4, v8, v4, v20
	v_fma_f32 v5, v8, v5, v21
	v_fma_f32 v6, v8, v6, v22
	v_fma_f32 v7, v8, v7, v23
	v_cvt_pk_bf16_f32 v64, v0, v1
	v_cvt_pk_bf16_f32 v65, v2, v3
	v_cvt_pk_bf16_f32 v66, v4, v5
	v_cvt_pk_bf16_f32 v67, v6, v7
	global_store_dwordx4 v10, v[64:67], s[14:15]
	s_add_u32 s14, s14, 0x40000
	s_addc_u32 s15, s15, 0
	s_waitcnt vmcnt(16)
	v_lshlrev_b32_e32 v16, 16, v68
	v_and_b32_e32 v17, 0xffff0000, v68
	v_lshlrev_b32_e32 v18, 16, v69
	v_and_b32_e32 v19, 0xffff0000, v69
	v_lshlrev_b32_e32 v20, 16, v70
	v_and_b32_e32 v21, 0xffff0000, v70
	v_lshlrev_b32_e32 v22, 16, v71
	v_and_b32_e32 v23, 0xffff0000, v71
	v_fma_f32 v0, v8, v0, v16
	v_fma_f32 v1, v8, v1, v17
	v_fma_f32 v2, v8, v2, v18
	v_fma_f32 v3, v8, v3, v19
	v_fma_f32 v4, v8, v4, v20
	v_fma_f32 v5, v8, v5, v21
	v_fma_f32 v6, v8, v6, v22
	v_fma_f32 v7, v8, v7, v23
	v_cvt_pk_bf16_f32 v68, v0, v1
	v_cvt_pk_bf16_f32 v69, v2, v3
	v_cvt_pk_bf16_f32 v70, v4, v5
	v_cvt_pk_bf16_f32 v71, v6, v7
	global_store_dwordx4 v10, v[68:71], s[14:15]
	s_add_u32 s14, s14, 0x40000
	s_addc_u32 s15, s15, 0
	s_waitcnt vmcnt(16)
	v_lshlrev_b32_e32 v16, 16, v72
	v_and_b32_e32 v17, 0xffff0000, v72
	v_lshlrev_b32_e32 v18, 16, v73
	v_and_b32_e32 v19, 0xffff0000, v73
	v_lshlrev_b32_e32 v20, 16, v74
	v_and_b32_e32 v21, 0xffff0000, v74
	v_lshlrev_b32_e32 v22, 16, v75
	v_and_b32_e32 v23, 0xffff0000, v75
	v_fma_f32 v0, v8, v0, v16
	v_fma_f32 v1, v8, v1, v17
	v_fma_f32 v2, v8, v2, v18
	v_fma_f32 v3, v8, v3, v19
	v_fma_f32 v4, v8, v4, v20
	v_fma_f32 v5, v8, v5, v21
	v_fma_f32 v6, v8, v6, v22
	v_fma_f32 v7, v8, v7, v23
	v_cvt_pk_bf16_f32 v72, v0, v1
	v_cvt_pk_bf16_f32 v73, v2, v3
	v_cvt_pk_bf16_f32 v74, v4, v5
	v_cvt_pk_bf16_f32 v75, v6, v7
	global_store_dwordx4 v10, v[72:75], s[14:15]
	s_add_u32 s14, s14, 0x40000
	s_addc_u32 s15, s15, 0
	s_waitcnt vmcnt(16)
	v_lshlrev_b32_e32 v16, 16, v76
	v_and_b32_e32 v17, 0xffff0000, v76
	v_lshlrev_b32_e32 v18, 16, v77
	v_and_b32_e32 v19, 0xffff0000, v77
	v_lshlrev_b32_e32 v20, 16, v78
	v_and_b32_e32 v21, 0xffff0000, v78
	v_lshlrev_b32_e32 v22, 16, v79
	v_and_b32_e32 v23, 0xffff0000, v79
	v_fma_f32 v0, v8, v0, v16
	v_fma_f32 v1, v8, v1, v17
	v_fma_f32 v2, v8, v2, v18
	v_fma_f32 v3, v8, v3, v19
	v_fma_f32 v4, v8, v4, v20
	v_fma_f32 v5, v8, v5, v21
	v_fma_f32 v6, v8, v6, v22
	v_fma_f32 v7, v8, v7, v23
	v_cvt_pk_bf16_f32 v76, v0, v1
	v_cvt_pk_bf16_f32 v77, v2, v3
	v_cvt_pk_bf16_f32 v78, v4, v5
	v_cvt_pk_bf16_f32 v79, v6, v7
	global_store_dwordx4 v10, v[76:79], s[14:15]
	s_add_u32 s14, s14, 0x40000
	s_addc_u32 s15, s15, 0
	s_waitcnt vmcnt(16)
	v_lshlrev_b32_e32 v16, 16, v80
	v_and_b32_e32 v17, 0xffff0000, v80
	v_lshlrev_b32_e32 v18, 16, v81
	v_and_b32_e32 v19, 0xffff0000, v81
	v_lshlrev_b32_e32 v20, 16, v82
	v_and_b32_e32 v21, 0xffff0000, v82
	v_lshlrev_b32_e32 v22, 16, v83
	v_and_b32_e32 v23, 0xffff0000, v83
	v_fma_f32 v0, v8, v0, v16
	v_fma_f32 v1, v8, v1, v17
	v_fma_f32 v2, v8, v2, v18
	v_fma_f32 v3, v8, v3, v19
	v_fma_f32 v4, v8, v4, v20
	v_fma_f32 v5, v8, v5, v21
	v_fma_f32 v6, v8, v6, v22
	v_fma_f32 v7, v8, v7, v23
	v_cvt_pk_bf16_f32 v80, v0, v1
	v_cvt_pk_bf16_f32 v81, v2, v3
	v_cvt_pk_bf16_f32 v82, v4, v5
	v_cvt_pk_bf16_f32 v83, v6, v7
	global_store_dwordx4 v10, v[80:83], s[14:15]
	s_waitcnt vmcnt(16)
	v_lshlrev_b32_e32 v16, 16, v84
	v_and_b32_e32 v17, 0xffff0000, v84
	v_lshlrev_b32_e32 v18, 16, v85
	v_and_b32_e32 v19, 0xffff0000, v85
	v_lshlrev_b32_e32 v20, 16, v86
	v_and_b32_e32 v21, 0xffff0000, v86
	v_lshlrev_b32_e32 v22, 16, v87
	v_and_b32_e32 v23, 0xffff0000, v87
	v_fma_f32 v0, v8, v0, v16
	v_fma_f32 v1, v8, v1, v17
	v_fma_f32 v2, v8, v2, v18
	v_fma_f32 v3, v8, v3, v19
	v_fma_f32 v4, v8, v4, v20
	v_fma_f32 v5, v8, v5, v21
	v_fma_f32 v6, v8, v6, v22
	v_fma_f32 v7, v8, v7, v23
	global_store_dword v11, v0, s[6:7] nt
	global_store_dword v11, v1, s[6:7] offset:1024 nt
	global_store_dword v11, v2, s[6:7] offset:2048 nt
	global_store_dword v11, v3, s[6:7] offset:3072 nt
	global_store_dword v12, v4, s[6:7] nt
	global_store_dword v12, v5, s[6:7] offset:1024 nt
	global_store_dword v12, v6, s[6:7] offset:2048 nt
	global_store_dword v12, v7, s[6:7] offset:3072 nt
